# batched residual epilogue also on the G2 instance (bf16-residual latent tiles, i.e. layer 1)
# speedup vs baseline: 1.0067x; 1.0021x over previous
; __device__ __forceinline__ unsigned cvt_pk_bf16(float lo, float hi) { unsigned r; asm volatile("v_cvt_pk_bf16_f32 %0, %1, %2" : "=v"(r) : "v"(lo), "v"(hi)); return r; }
;     __device__ __forceinline__ void operator()(const f32x4 (&acc)[2][2][4][2], const Unit& u, int wr, int wc, int fr, int fq) const {
;         const bool lat = u.pm < NLAT / BM; const int bb = lat ? (u.pm >> 5) : 4;
;         const int row0 = (lat ? u.pm * BM : u.pm * BM - NLAT) + wr * 64 + fr, col0 = u.pn * BM + wc * 32 + 8 * fq;
;         f32x4 g[2][2];
; #pragma unroll
;         for (int bj = 0; bj < 2; ++bj)
; #pragma unroll
;             for (int n = 0; n < 2; ++n) g[bj][n] = *(const f32x4*)(gate + bb * 6144 + col0 + bj * HALF + n * 4);
; #pragma unroll
;         for (int ai = 0; ai < 2; ++ai)
; #pragma unroll
;             for (int m = 0; m < 4; ++m) {
;                 const size_t off = (size_t)(row0 + ai * HALF + m * 16) * 1024 + col0;
; #pragma unroll
;                 for (int bj = 0; bj < 2; ++bj) {
;                     f32x4 b0, b1;
;                     if (!lat) { b0 = *(const f32x4*)(baseC + off + bj * HALF); b1 = *(const f32x4*)(baseC + off + bj * HALF + 4); }
;                     else if (baseLf) { b0 = *(const f32x4*)(baseLf + off + bj * HALF); b1 = *(const f32x4*)(baseLf + off + bj * HALF + 4); }
;                     else { const u32x4 w = *(const u32x4*)(baseLb + off + bj * HALF);
;                         b0 = (f32x4){__builtin_bit_cast(float, w.x << 16), __builtin_bit_cast(float, w.x & 0xffff0000u), __builtin_bit_cast(float, w.y << 16), __builtin_bit_cast(float, w.y & 0xffff0000u)};
;                         b1 = (f32x4){__builtin_bit_cast(float, w.z << 16), __builtin_bit_cast(float, w.z & 0xffff0000u), __builtin_bit_cast(float, w.w << 16), __builtin_bit_cast(float, w.w & 0xffff0000u)}; }
;                     const f32x4 o0 = b0 + g[bj][0] * acc[ai][bj][m][0], o1 = b1 + g[bj][1] * acc[ai][bj][m][1];
;                     if (!lat) { *(f32x4*)(outC + off + bj * HALF) = o0; *(f32x4*)(outC + off + bj * HALF + 4) = o1; }
;                     else { u32x4 w; w.x = cvt_pk_bf16(o0.x, o0.y); w.y = cvt_pk_bf16(o0.z, o0.w); w.z = cvt_pk_bf16(o1.x, o1.y); w.w = cvt_pk_bf16(o1.z, o1.w); *(u32x4*)(outL + off + bj * HALF) = w; }
;                 }
;             }
;     }
.LBB0_565:
	s_cmpk_gt_i32 s42, 0x7f
	s_cselect_b64 s[48:49], -1, 0
	s_lshl_b32 s15, s42, 8
	s_lshr_b32 s14, s42, 5
	s_add_i32 s16, s15, 0xffff8000
	s_cmpk_lt_i32 s42, 0x80
	s_cselect_b64 s[12:13], -1, 0
	s_mulk_i32 s14, 0x1800
	s_and_b64 vcc, s[12:13], exec
	s_cselect_b32 s12, s14, 0x6000
	s_cselect_b32 s14, s15, s16
	s_ashr_i32 s13, s12, 31
	s_lshl_b64 s[12:13], s[12:13], 2
	v_lshl_or_b32 v162, s40, 8, v172
	s_add_u32 s12, s69, s12
	s_addc_u32 s13, s93, s13
	v_ashrrev_i32_e32 v163, 31, v162
	v_lshl_add_u64 v[44:45], v[162:163], 2, s[12:13]
	global_load_dwordx4 v[56:59], v[44:45], off offset:16
	global_load_dwordx4 v[60:63], v[44:45], off
	global_load_dwordx4 v[40:43], v[44:45], off offset:528
	s_nop 0
	global_load_dwordx4 v[44:47], v[44:45], off offset:512
	v_add_u32_e32 v164, s14, v170
	v_ashrrev_i32_e32 v165, 31, v164
	v_lshlrev_b64 v[144:145], 10, v[164:165]
	v_lshl_add_u64 v[166:167], v[144:145], 0, v[162:163]
	s_mov_b64 s[40:41], -1
	v_lshl_add_u64 v[168:169], v[166:167], 2, s[46:47]
	s_or_b64 s[14:15], s[48:49], s[52:53]
	s_cmp_eq_u64 s[14:15], 0
	s_cbranch_scc0 .Lep2_slow
	v_lshl_add_u64 v[168:169], v[166:167], 1, s[6:7]
	s_mov_b64 s[12:13], 0x8000
	s_mov_b64 s[14:15], 0x28000
	v_mov_b32_e32 v164, v168
	v_mov_b32_e32 v165, v169
	global_load_dwordx4 v[174:177], v[168:169], off
	global_load_dwordx4 v[178:181], v[168:169], off offset:256
	v_lshl_add_u64 v[168:169], v[168:169], 0, s[12:13]
	global_load_dwordx4 v[182:185], v[168:169], off
	global_load_dwordx4 v[186:189], v[168:169], off offset:256
	v_lshl_add_u64 v[168:169], v[168:169], 0, s[12:13]
	global_load_dwordx4 v[190:193], v[168:169], off
	global_load_dwordx4 v[194:197], v[168:169], off offset:256
	v_lshl_add_u64 v[168:169], v[168:169], 0, s[12:13]
	global_load_dwordx4 v[198:201], v[168:169], off
	global_load_dwordx4 v[202:205], v[168:169], off offset:256
	s_waitcnt vmcnt(7)
	v_lshlrev_b32_e32 v144, 16, v174
	v_and_b32_e32 v145, 0xffff0000, v174
	v_lshlrev_b32_e32 v146, 16, v175
	v_and_b32_e32 v147, 0xffff0000, v175
	v_lshlrev_b32_e32 v148, 16, v176
	v_and_b32_e32 v149, 0xffff0000, v176
	v_lshlrev_b32_e32 v150, 16, v177
	v_and_b32_e32 v151, 0xffff0000, v177
	v_lshl_add_u64 v[168:169], v[168:169], 0, s[14:15]
	global_load_dwordx4 v[174:177], v[168:169], off
	v_pk_fma_f32 v[140:141], v[140:141], v[60:61], v[144:145]
	v_pk_fma_f32 v[142:143], v[142:143], v[62:63], v[146:147]
	v_pk_fma_f32 v[136:137], v[136:137], v[56:57], v[148:149]
	v_pk_fma_f32 v[138:139], v[138:139], v[58:59], v[150:151]
	v_cvt_pk_bf16_f32 v140, v140, v141
	v_cvt_pk_bf16_f32 v141, v142, v143
	v_cvt_pk_bf16_f32 v142, v136, v137
	v_cvt_pk_bf16_f32 v143, v138, v139
	s_waitcnt vmcnt(7)
	v_lshlrev_b32_e32 v144, 16, v178
	v_and_b32_e32 v145, 0xffff0000, v178
	v_lshlrev_b32_e32 v146, 16, v179
	v_and_b32_e32 v147, 0xffff0000, v179
	v_lshlrev_b32_e32 v148, 16, v180
	v_and_b32_e32 v149, 0xffff0000, v180
	v_lshlrev_b32_e32 v150, 16, v181
	v_and_b32_e32 v151, 0xffff0000, v181
	global_load_dwordx4 v[178:181], v[168:169], off offset:256
	v_pk_fma_f32 v[132:133], v[132:133], v[44:45], v[144:145]
	v_pk_fma_f32 v[134:135], v[134:135], v[46:47], v[146:147]
	v_pk_fma_f32 v[128:129], v[128:129], v[40:41], v[148:149]
	v_pk_fma_f32 v[130:131], v[130:131], v[42:43], v[150:151]
	v_cvt_pk_bf16_f32 v132, v132, v133
	v_cvt_pk_bf16_f32 v133, v134, v135
	v_cvt_pk_bf16_f32 v134, v128, v129
	v_cvt_pk_bf16_f32 v135, v130, v131
	s_waitcnt vmcnt(7)
	v_lshlrev_b32_e32 v144, 16, v182
	v_and_b32_e32 v145, 0xffff0000, v182
	v_lshlrev_b32_e32 v146, 16, v183
	v_and_b32_e32 v147, 0xffff0000, v183
	v_lshlrev_b32_e32 v148, 16, v184
	v_and_b32_e32 v149, 0xffff0000, v184
	v_lshlrev_b32_e32 v150, 16, v185
	v_and_b32_e32 v151, 0xffff0000, v185
	v_lshl_add_u64 v[168:169], v[168:169], 0, s[12:13]
	global_load_dwordx4 v[182:185], v[168:169], off
	v_pk_fma_f32 v[124:125], v[124:125], v[60:61], v[144:145]
	v_pk_fma_f32 v[126:127], v[126:127], v[62:63], v[146:147]
	v_pk_fma_f32 v[120:121], v[120:121], v[56:57], v[148:149]
	v_pk_fma_f32 v[122:123], v[122:123], v[58:59], v[150:151]
	v_cvt_pk_bf16_f32 v124, v124, v125
	v_cvt_pk_bf16_f32 v125, v126, v127
	v_cvt_pk_bf16_f32 v126, v120, v121
	v_cvt_pk_bf16_f32 v127, v122, v123
	s_waitcnt vmcnt(7)
	v_lshlrev_b32_e32 v144, 16, v186
	v_and_b32_e32 v145, 0xffff0000, v186
	v_lshlrev_b32_e32 v146, 16, v187
	v_and_b32_e32 v147, 0xffff0000, v187
	v_lshlrev_b32_e32 v148, 16, v188
	v_and_b32_e32 v149, 0xffff0000, v188
	v_lshlrev_b32_e32 v150, 16, v189
	v_and_b32_e32 v151, 0xffff0000, v189
	global_load_dwordx4 v[186:189], v[168:169], off offset:256
	v_pk_fma_f32 v[116:117], v[116:117], v[44:45], v[144:145]
	v_pk_fma_f32 v[118:119], v[118:119], v[46:47], v[146:147]
	v_pk_fma_f32 v[112:113], v[112:113], v[40:41], v[148:149]
	v_pk_fma_f32 v[114:115], v[114:115], v[42:43], v[150:151]
	v_cvt_pk_bf16_f32 v116, v116, v117
	v_cvt_pk_bf16_f32 v117, v118, v119
	v_cvt_pk_bf16_f32 v118, v112, v113
	v_cvt_pk_bf16_f32 v119, v114, v115
	s_waitcnt vmcnt(7)
	v_lshlrev_b32_e32 v144, 16, v190
	v_and_b32_e32 v145, 0xffff0000, v190
	v_lshlrev_b32_e32 v146, 16, v191
	v_and_b32_e32 v147, 0xffff0000, v191
	v_lshlrev_b32_e32 v148, 16, v192
	v_and_b32_e32 v149, 0xffff0000, v192
	v_lshlrev_b32_e32 v150, 16, v193
	v_and_b32_e32 v151, 0xffff0000, v193
	v_lshl_add_u64 v[168:169], v[168:169], 0, s[12:13]
	global_load_dwordx4 v[190:193], v[168:169], off
	v_pk_fma_f32 v[108:109], v[108:109], v[60:61], v[144:145]
	v_pk_fma_f32 v[110:111], v[110:111], v[62:63], v[146:147]
	v_pk_fma_f32 v[104:105], v[104:105], v[56:57], v[148:149]
	v_pk_fma_f32 v[106:107], v[106:107], v[58:59], v[150:151]
	v_cvt_pk_bf16_f32 v108, v108, v109
	v_cvt_pk_bf16_f32 v109, v110, v111
	v_cvt_pk_bf16_f32 v110, v104, v105
	v_cvt_pk_bf16_f32 v111, v106, v107
	s_waitcnt vmcnt(7)
; __device__ __forceinline__ unsigned cvt_pk_bf16(float lo, float hi) { unsigned r; asm volatile("v_cvt_pk_bf16_f32 %0, %1, %2" : "=v"(r) : "v"(lo), "v"(hi)); return r; }
;     __device__ __forceinline__ void operator()(const f32x4 (&acc)[2][2][4][2], const Unit& u, int wr, int wc, int fr, int fq) const {
;     ...
;                 for (int bj = 0; bj < 2; ++bj) {
;                     f32x4 b0, b1;
;                     if (!lat) { b0 = *(const f32x4*)(baseC + off + bj * HALF); b1 = *(const f32x4*)(baseC + off + bj * HALF + 4); }
;                     else if (baseLf) { b0 = *(const f32x4*)(baseLf + off + bj * HALF); b1 = *(const f32x4*)(baseLf + off + bj * HALF + 4); }
;                     else { const u32x4 w = *(const u32x4*)(baseLb + off + bj * HALF);
;                         b0 = (f32x4){__builtin_bit_cast(float, w.x << 16), __builtin_bit_cast(float, w.x & 0xffff0000u), __builtin_bit_cast(float, w.y << 16), __builtin_bit_cast(float, w.y & 0xffff0000u)};
;                         b1 = (f32x4){__builtin_bit_cast(float, w.z << 16), __builtin_bit_cast(float, w.z & 0xffff0000u), __builtin_bit_cast(float, w.w << 16), __builtin_bit_cast(float, w.w & 0xffff0000u)}; }
;                     const f32x4 o0 = b0 + g[bj][0] * acc[ai][bj][m][0], o1 = b1 + g[bj][1] * acc[ai][bj][m][1];
;                     if (!lat) { *(f32x4*)(outC + off + bj * HALF) = o0; *(f32x4*)(outC + off + bj * HALF + 4) = o1; }
;                     else { u32x4 w; w.x = cvt_pk_bf16(o0.x, o0.y); w.y = cvt_pk_bf16(o0.z, o0.w); w.z = cvt_pk_bf16(o1.x, o1.y); w.w = cvt_pk_bf16(o1.z, o1.w); *(u32x4*)(outL + off + bj * HALF) = w; }
;                 }
	v_lshlrev_b32_e32 v144, 16, v194
	v_and_b32_e32 v145, 0xffff0000, v194
	v_lshlrev_b32_e32 v146, 16, v195
	v_and_b32_e32 v147, 0xffff0000, v195
	v_lshlrev_b32_e32 v148, 16, v196
	v_and_b32_e32 v149, 0xffff0000, v196
	v_lshlrev_b32_e32 v150, 16, v197
	v_and_b32_e32 v151, 0xffff0000, v197
	global_load_dwordx4 v[194:197], v[168:169], off offset:256
	v_pk_fma_f32 v[100:101], v[100:101], v[44:45], v[144:145]
	v_pk_fma_f32 v[102:103], v[102:103], v[46:47], v[146:147]
	v_pk_fma_f32 v[96:97], v[96:97], v[40:41], v[148:149]
	v_pk_fma_f32 v[98:99], v[98:99], v[42:43], v[150:151]
	v_cvt_pk_bf16_f32 v100, v100, v101
	v_cvt_pk_bf16_f32 v101, v102, v103
	v_cvt_pk_bf16_f32 v102, v96, v97
	v_cvt_pk_bf16_f32 v103, v98, v99
	s_waitcnt vmcnt(7)
	v_lshlrev_b32_e32 v144, 16, v198
	v_and_b32_e32 v145, 0xffff0000, v198
	v_lshlrev_b32_e32 v146, 16, v199
	v_and_b32_e32 v147, 0xffff0000, v199
	v_lshlrev_b32_e32 v148, 16, v200
	v_and_b32_e32 v149, 0xffff0000, v200
	v_lshlrev_b32_e32 v150, 16, v201
	v_and_b32_e32 v151, 0xffff0000, v201
	v_lshl_add_u64 v[168:169], v[168:169], 0, s[12:13]
	global_load_dwordx4 v[198:201], v[168:169], off
	v_pk_fma_f32 v[92:93], v[92:93], v[60:61], v[144:145]
	v_pk_fma_f32 v[94:95], v[94:95], v[62:63], v[146:147]
	v_pk_fma_f32 v[88:89], v[88:89], v[56:57], v[148:149]
	v_pk_fma_f32 v[90:91], v[90:91], v[58:59], v[150:151]
	v_cvt_pk_bf16_f32 v92, v92, v93
	v_cvt_pk_bf16_f32 v93, v94, v95
	v_cvt_pk_bf16_f32 v94, v88, v89
	v_cvt_pk_bf16_f32 v95, v90, v91
	s_waitcnt vmcnt(7)
	v_lshlrev_b32_e32 v144, 16, v202
	v_and_b32_e32 v145, 0xffff0000, v202
	v_lshlrev_b32_e32 v146, 16, v203
	v_and_b32_e32 v147, 0xffff0000, v203
	v_lshlrev_b32_e32 v148, 16, v204
	v_and_b32_e32 v149, 0xffff0000, v204
	v_lshlrev_b32_e32 v150, 16, v205
	v_and_b32_e32 v151, 0xffff0000, v205
	global_load_dwordx4 v[202:205], v[168:169], off offset:256
	v_pk_fma_f32 v[84:85], v[84:85], v[44:45], v[144:145]
	v_pk_fma_f32 v[86:87], v[86:87], v[46:47], v[146:147]
	v_pk_fma_f32 v[80:81], v[80:81], v[40:41], v[148:149]
	v_pk_fma_f32 v[82:83], v[82:83], v[42:43], v[150:151]
	v_cvt_pk_bf16_f32 v84, v84, v85
	v_cvt_pk_bf16_f32 v85, v86, v87
	v_cvt_pk_bf16_f32 v86, v80, v81
	v_cvt_pk_bf16_f32 v87, v82, v83
	s_waitcnt vmcnt(7)
	v_lshlrev_b32_e32 v144, 16, v174
	v_and_b32_e32 v145, 0xffff0000, v174
	v_lshlrev_b32_e32 v146, 16, v175
	v_and_b32_e32 v147, 0xffff0000, v175
	v_lshlrev_b32_e32 v148, 16, v176
	v_and_b32_e32 v149, 0xffff0000, v176
	v_lshlrev_b32_e32 v150, 16, v177
	v_and_b32_e32 v151, 0xffff0000, v177
	v_pk_fma_f32 v[76:77], v[76:77], v[60:61], v[144:145]
	v_pk_fma_f32 v[78:79], v[78:79], v[62:63], v[146:147]
	v_pk_fma_f32 v[72:73], v[72:73], v[56:57], v[148:149]
	v_pk_fma_f32 v[74:75], v[74:75], v[58:59], v[150:151]
	v_cvt_pk_bf16_f32 v76, v76, v77
	v_cvt_pk_bf16_f32 v77, v78, v79
	v_cvt_pk_bf16_f32 v78, v72, v73
	v_cvt_pk_bf16_f32 v79, v74, v75
	s_waitcnt vmcnt(6)
	v_lshlrev_b32_e32 v144, 16, v178
	v_and_b32_e32 v145, 0xffff0000, v178
	v_lshlrev_b32_e32 v146, 16, v179
	v_and_b32_e32 v147, 0xffff0000, v179
	v_lshlrev_b32_e32 v148, 16, v180
	v_and_b32_e32 v149, 0xffff0000, v180
	v_lshlrev_b32_e32 v150, 16, v181
	v_and_b32_e32 v151, 0xffff0000, v181
	v_pk_fma_f32 v[68:69], v[68:69], v[44:45], v[144:145]
	v_pk_fma_f32 v[70:71], v[70:71], v[46:47], v[146:147]
	v_pk_fma_f32 v[64:65], v[64:65], v[40:41], v[148:149]
	v_pk_fma_f32 v[66:67], v[66:67], v[42:43], v[150:151]
	v_cvt_pk_bf16_f32 v68, v68, v69
	v_cvt_pk_bf16_f32 v69, v70, v71
	v_cvt_pk_bf16_f32 v70, v64, v65
	v_cvt_pk_bf16_f32 v71, v66, v67
	s_waitcnt vmcnt(5)
	v_lshlrev_b32_e32 v144, 16, v182
	v_and_b32_e32 v145, 0xffff0000, v182
	v_lshlrev_b32_e32 v146, 16, v183
	v_and_b32_e32 v147, 0xffff0000, v183
	v_lshlrev_b32_e32 v148, 16, v184
	v_and_b32_e32 v149, 0xffff0000, v184
	v_lshlrev_b32_e32 v150, 16, v185
	v_and_b32_e32 v151, 0xffff0000, v185
	v_pk_fma_f32 v[52:53], v[52:53], v[60:61], v[144:145]
	v_pk_fma_f32 v[54:55], v[54:55], v[62:63], v[146:147]
	v_pk_fma_f32 v[48:49], v[48:49], v[56:57], v[148:149]
	v_pk_fma_f32 v[50:51], v[50:51], v[58:59], v[150:151]
	v_cvt_pk_bf16_f32 v52, v52, v53
	v_cvt_pk_bf16_f32 v53, v54, v55
	v_cvt_pk_bf16_f32 v54, v48, v49
	v_cvt_pk_bf16_f32 v55, v50, v51
	s_waitcnt vmcnt(4)
; __device__ __forceinline__ unsigned cvt_pk_bf16(float lo, float hi) { unsigned r; asm volatile("v_cvt_pk_bf16_f32 %0, %1, %2" : "=v"(r) : "v"(lo), "v"(hi)); return r; }
;     __device__ __forceinline__ void operator()(const f32x4 (&acc)[2][2][4][2], const Unit& u, int wr, int wc, int fr, int fq) const {
;     ...
;                 for (int bj = 0; bj < 2; ++bj) {
;                     f32x4 b0, b1;
;                     if (!lat) { b0 = *(const f32x4*)(baseC + off + bj * HALF); b1 = *(const f32x4*)(baseC + off + bj * HALF + 4); }
;                     else if (baseLf) { b0 = *(const f32x4*)(baseLf + off + bj * HALF); b1 = *(const f32x4*)(baseLf + off + bj * HALF + 4); }
;                     else { const u32x4 w = *(const u32x4*)(baseLb + off + bj * HALF);
;                         b0 = (f32x4){__builtin_bit_cast(float, w.x << 16), __builtin_bit_cast(float, w.x & 0xffff0000u), __builtin_bit_cast(float, w.y << 16), __builtin_bit_cast(float, w.y & 0xffff0000u)};
;                         b1 = (f32x4){__builtin_bit_cast(float, w.z << 16), __builtin_bit_cast(float, w.z & 0xffff0000u), __builtin_bit_cast(float, w.w << 16), __builtin_bit_cast(float, w.w & 0xffff0000u)}; }
;                     const f32x4 o0 = b0 + g[bj][0] * acc[ai][bj][m][0], o1 = b1 + g[bj][1] * acc[ai][bj][m][1];
;                     if (!lat) { *(f32x4*)(outC + off + bj * HALF) = o0; *(f32x4*)(outC + off + bj * HALF + 4) = o1; }
;                     else { u32x4 w; w.x = cvt_pk_bf16(o0.x, o0.y); w.y = cvt_pk_bf16(o0.z, o0.w); w.z = cvt_pk_bf16(o1.x, o1.y); w.w = cvt_pk_bf16(o1.z, o1.w); *(u32x4*)(outL + off + bj * HALF) = w; }
;                 }
	v_lshlrev_b32_e32 v144, 16, v186
	v_and_b32_e32 v145, 0xffff0000, v186
	v_lshlrev_b32_e32 v146, 16, v187
	v_and_b32_e32 v147, 0xffff0000, v187
	v_lshlrev_b32_e32 v148, 16, v188
	v_and_b32_e32 v149, 0xffff0000, v188
	v_lshlrev_b32_e32 v150, 16, v189
	v_and_b32_e32 v151, 0xffff0000, v189
	v_pk_fma_f32 v[36:37], v[36:37], v[44:45], v[144:145]
	v_pk_fma_f32 v[38:39], v[38:39], v[46:47], v[146:147]
	v_pk_fma_f32 v[32:33], v[32:33], v[40:41], v[148:149]
	v_pk_fma_f32 v[34:35], v[34:35], v[42:43], v[150:151]
	v_cvt_pk_bf16_f32 v36, v36, v37
	v_cvt_pk_bf16_f32 v37, v38, v39
	v_cvt_pk_bf16_f32 v38, v32, v33
	v_cvt_pk_bf16_f32 v39, v34, v35
	s_waitcnt vmcnt(3)
	v_lshlrev_b32_e32 v144, 16, v190
	v_and_b32_e32 v145, 0xffff0000, v190
	v_lshlrev_b32_e32 v146, 16, v191
	v_and_b32_e32 v147, 0xffff0000, v191
	v_lshlrev_b32_e32 v148, 16, v192
	v_and_b32_e32 v149, 0xffff0000, v192
	v_lshlrev_b32_e32 v150, 16, v193
	v_and_b32_e32 v151, 0xffff0000, v193
	v_pk_fma_f32 v[28:29], v[28:29], v[60:61], v[144:145]
	v_pk_fma_f32 v[30:31], v[30:31], v[62:63], v[146:147]
	v_pk_fma_f32 v[24:25], v[24:25], v[56:57], v[148:149]
	v_pk_fma_f32 v[26:27], v[26:27], v[58:59], v[150:151]
	v_cvt_pk_bf16_f32 v28, v28, v29
	v_cvt_pk_bf16_f32 v29, v30, v31
	v_cvt_pk_bf16_f32 v30, v24, v25
	v_cvt_pk_bf16_f32 v31, v26, v27
	s_waitcnt vmcnt(2)
	v_lshlrev_b32_e32 v144, 16, v194
	v_and_b32_e32 v145, 0xffff0000, v194
	v_lshlrev_b32_e32 v146, 16, v195
	v_and_b32_e32 v147, 0xffff0000, v195
	v_lshlrev_b32_e32 v148, 16, v196
	v_and_b32_e32 v149, 0xffff0000, v196
	v_lshlrev_b32_e32 v150, 16, v197
	v_and_b32_e32 v151, 0xffff0000, v197
	v_pk_fma_f32 v[20:21], v[20:21], v[44:45], v[144:145]
	v_pk_fma_f32 v[22:23], v[22:23], v[46:47], v[146:147]
	v_pk_fma_f32 v[16:17], v[16:17], v[40:41], v[148:149]
	v_pk_fma_f32 v[18:19], v[18:19], v[42:43], v[150:151]
	v_cvt_pk_bf16_f32 v20, v20, v21
	v_cvt_pk_bf16_f32 v21, v22, v23
	v_cvt_pk_bf16_f32 v22, v16, v17
	v_cvt_pk_bf16_f32 v23, v18, v19
	s_waitcnt vmcnt(1)
	v_lshlrev_b32_e32 v144, 16, v198
	v_and_b32_e32 v145, 0xffff0000, v198
	v_lshlrev_b32_e32 v146, 16, v199
	v_and_b32_e32 v147, 0xffff0000, v199
	v_lshlrev_b32_e32 v148, 16, v200
	v_and_b32_e32 v149, 0xffff0000, v200
	v_lshlrev_b32_e32 v150, 16, v201
	v_and_b32_e32 v151, 0xffff0000, v201
	v_pk_fma_f32 v[12:13], v[12:13], v[60:61], v[144:145]
	v_pk_fma_f32 v[14:15], v[14:15], v[62:63], v[146:147]
	v_pk_fma_f32 v[8:9], v[8:9], v[56:57], v[148:149]
	v_pk_fma_f32 v[10:11], v[10:11], v[58:59], v[150:151]
	v_cvt_pk_bf16_f32 v12, v12, v13
	v_cvt_pk_bf16_f32 v13, v14, v15
	v_cvt_pk_bf16_f32 v14, v8, v9
	v_cvt_pk_bf16_f32 v15, v10, v11
	s_waitcnt vmcnt(0)
	v_lshlrev_b32_e32 v144, 16, v202
	v_and_b32_e32 v145, 0xffff0000, v202
	v_lshlrev_b32_e32 v146, 16, v203
	v_and_b32_e32 v147, 0xffff0000, v203
	v_lshlrev_b32_e32 v148, 16, v204
	v_and_b32_e32 v149, 0xffff0000, v204
	v_lshlrev_b32_e32 v150, 16, v205
	v_and_b32_e32 v151, 0xffff0000, v205
	v_pk_fma_f32 v[4:5], v[4:5], v[44:45], v[144:145]
	v_pk_fma_f32 v[6:7], v[6:7], v[46:47], v[146:147]
	v_pk_fma_f32 v[0:1], v[0:1], v[40:41], v[148:149]
	v_pk_fma_f32 v[2:3], v[2:3], v[42:43], v[150:151]
	v_cvt_pk_bf16_f32 v4, v4, v5
	v_cvt_pk_bf16_f32 v5, v6, v7
	v_cvt_pk_bf16_f32 v6, v0, v1
	v_cvt_pk_bf16_f32 v7, v2, v3
	global_store_dwordx4 v[164:165], v[140:143], off
	global_store_dwordx4 v[164:165], v[132:135], off offset:256
	v_lshl_add_u64 v[164:165], v[164:165], 0, s[12:13]
	global_store_dwordx4 v[164:165], v[124:127], off
	global_store_dwordx4 v[164:165], v[116:119], off offset:256
	v_lshl_add_u64 v[164:165], v[164:165], 0, s[12:13]
	global_store_dwordx4 v[164:165], v[108:111], off
	global_store_dwordx4 v[164:165], v[100:103], off offset:256
	v_lshl_add_u64 v[164:165], v[164:165], 0, s[12:13]
	global_store_dwordx4 v[164:165], v[92:95], off
	global_store_dwordx4 v[164:165], v[84:87], off offset:256
	v_lshl_add_u64 v[164:165], v[164:165], 0, s[14:15]
	global_store_dwordx4 v[164:165], v[76:79], off
	global_store_dwordx4 v[164:165], v[68:71], off offset:256
	v_lshl_add_u64 v[164:165], v[164:165], 0, s[12:13]
	global_store_dwordx4 v[164:165], v[52:55], off
	global_store_dwordx4 v[164:165], v[36:39], off offset:256
	v_lshl_add_u64 v[164:165], v[164:165], 0, s[12:13]
	global_store_dwordx4 v[164:165], v[28:31], off
	global_store_dwordx4 v[164:165], v[20:23], off offset:256
	v_lshl_add_u64 v[164:165], v[164:165], 0, s[12:13]
	global_store_dwordx4 v[164:165], v[12:15], off
	global_store_dwordx4 v[164:165], v[4:7], off offset:256
	s_mov_b64 s[40:41], -1
	s_mov_b64 s[48:49], -1
	s_branch .Lep2_join
.Lep2_slow:
	s_cbranch_vccnz .LBB0_567
	global_load_dwordx4 v[144:147], v[168:169], off offset:16
	global_load_dwordx4 v[148:151], v[168:169], off
	s_mov_b64 s[40:41], 0

; __device__ __forceinline__ unsigned cvt_pk_bf16(float lo, float hi) { unsigned r; asm volatile("v_cvt_pk_bf16_f32 %0, %1, %2" : "=v"(r) : "v"(lo), "v"(hi)); return r; }
;     __device__ __forceinline__ void operator()(const f32x4 (&acc)[2][2][4][2], const Unit& u, int wr, int wc, int fr, int fq) const {
;     ...
;                     const f32x4 o0 = b0 + g[bj][0] * acc[ai][bj][m][0], o1 = b1 + g[bj][1] * acc[ai][bj][m][1];
;                     if (!lat) { *(f32x4*)(outC + off + bj * HALF) = o0; *(f32x4*)(outC + off + bj * HALF + 4) = o1; }
;                     else { u32x4 w; w.x = cvt_pk_bf16(o0.x, o0.y); w.y = cvt_pk_bf16(o0.z, o0.w); w.z = cvt_pk_bf16(o1.x, o1.y); w.w = cvt_pk_bf16(o1.z, o1.w); *(u32x4*)(outL + off + bj * HALF) = w; }
;                 }
; template <class Epi, class Sched, bool ALIGN_EPI = false, bool SP2 = false>
; __device__ __forceinline__ void gemm_phase(PG8_LAS unsigned char* lds, const Gemm g, const Sched& S, const Epi& E) {
;     ...
;         if constexpr (!Epi::AFTER_DRAIN) { E(acc, cur, wr, wc, fr, fq); S.done(cur); }
;         if (!has_next) break;
.LBB0_725:
	v_cvt_pk_bf16_f32 v4, v4, v5
	v_cvt_pk_bf16_f32 v5, v6, v7
	v_cvt_pk_bf16_f32 v6, v0, v1
	v_cvt_pk_bf16_f32 v7, v2, v3
	global_store_dwordx4 v[16:17], v[4:7], off offset:256
.Lep2_join:
	s_andn2_b64 vcc, exec, s[38:39]
	s_mov_b64 s[38:39], -1
	s_cbranch_vccnz .LBB0_558
